# attention phases: static s_setprio 1 for waves 4-7 set at the unit-loop entry (reset by the next GEMM phase end)
# speedup vs baseline: 1.0025x; 1.0025x over previous
.LBB0_339:
	s_cmp_lt_i32 s4, 1
	s_cbranch_scc1 .LBB0_624
	v_readlane_b32 s0, v253, 51
	v_readlane_b32 s2, v255, 32
	v_readlane_b32 s1, v253, 52
	v_readlane_b32 s3, v255, 33
	s_and_b64 s[0:1], s[0:1], s[2:3]
	v_writelane_b32 v255, s0, 47
	s_nop 1
	v_writelane_b32 v255, s1, 48
	s_nop 0
	v_readlane_b32 s0, v255, 40
	v_readlane_b32 s1, v255, 41
	s_load_dwordx2 s[0:1], s[0:1], 0xe0
	s_waitcnt lgkmcnt(0)
	s_add_u32 s2, s0, 0xa074000
	v_writelane_b32 v255, s2, 49
	s_addc_u32 s2, s1, 0
	v_writelane_b32 v255, s2, 50
	s_add_u32 s2, s0, 0xa674000
	v_writelane_b32 v255, s2, 51
	s_addc_u32 s2, s1, 0
	v_writelane_b32 v255, s2, 52
	s_add_u32 s2, s0, 0x7634000
	v_writelane_b32 v255, s2, 53
	s_addc_u32 s2, s1, 0
	v_writelane_b32 v255, s2, 54
	s_add_u32 s0, s0, 0x7834000
	v_writelane_b32 v255, s0, 55
	s_addc_u32 s0, s1, 0
	v_writelane_b32 v255, s0, 56
	s_mov_b32 s0, 0
	v_writelane_b32 v255, s0, 57
	v_writelane_b32 v255, s4, 58
	v_readfirstlane_b32 s0, v179
	s_cmpk_lt_u32 s0, 0x100
	s_cbranch_scc1 .Lattn_prio_done
	s_setprio 1
.Lattn_prio_done:
	s_branch .LBB0_343
